# grid barrier: non-leader workgroups poll the cross-XCC release word directly; leader's per-XCC forwarding atomic dropped
# baseline (speedup 1.0000x reference)
.LBB0_58:
	s_or_b64 exec, exec, s[8:9]
	v_cvt_f32_u32_e32 v4, v2
	s_waitcnt vmcnt(0)
	v_readfirstlane_b32 s6, v3
	v_sub_u32_e32 v3, 0, v2
	v_rcp_iflag_f32_e32 v4, v4
	v_add_u32_e32 v5, s6, v1
	v_mul_f32_e32 v4, 0x4f7ffffe, v4
	v_cvt_u32_f32_e32 v4, v4
	v_mul_lo_u32 v1, v3, v4
	v_mul_hi_u32 v1, v4, v1
	v_add_u32_e32 v1, v4, v1
	v_mul_hi_u32 v1, v5, v1
	v_mul_lo_u32 v3, v1, v2
	v_sub_u32_e32 v3, v5, v3
	v_add_u32_e32 v4, 1, v1
	v_cmp_ge_u32_e32 vcc, v3, v2
	s_nop 1
	v_cndmask_b32_e32 v1, v1, v4, vcc
	v_sub_u32_e32 v4, v3, v2
	v_cndmask_b32_e32 v3, v3, v4, vcc
	v_add_u32_e32 v4, 1, v1
	v_cmp_ge_u32_e32 vcc, v3, v2
	v_add_u32_e32 v3, 1, v5
	s_nop 0
	v_cndmask_b32_e32 v1, v1, v4, vcc
	v_mul_lo_u32 v4, v2, v1
	v_add_u32_e32 v2, v4, v2
	v_cmp_ne_u32_e32 vcc, v3, v2
	s_and_saveexec_b64 s[6:7], vcc
	s_xor_b64 s[6:7], exec, s[6:7]
	s_cbranch_execz .LBB0_72
	s_waitcnt lgkmcnt(0)
	s_add_u32 s12, s2, 0x3c3500
	s_addc_u32 s13, s3, 0
	v_mov_b32_e32 v0, 0
	global_load_dword v0, v0, s[12:13] sc1
	s_waitcnt vmcnt(0)
	v_cmp_eq_u32_e32 vcc, v0, v1
	s_and_saveexec_b64 s[8:9], vcc
	s_cbranch_execz .LBB0_71
	s_add_u32 s10, s2, 0x3c0200
	s_addc_u32 s11, s3, 0
	s_mov_b32 s24, 1
	s_mov_b64 s[14:15], 0
	v_mov_b32_e32 v0, 0
	s_branch .LBB0_62

.LBB0_89:
	s_or_b64 exec, exec, s[2:3]
	s_mov_b64 s[2:3], exec
	v_mbcnt_lo_u32_b32 v0, s2, 0
	v_mbcnt_hi_u32_b32 v0, s3, v0
	v_cmp_eq_u32_e32 vcc, 0, v0
	s_waitcnt vmcnt(0)
	buffer_inv sc1
	s_and_saveexec_b64 s[6:7], vcc
	s_cbranch_execz .LBB0_91
	s_bcnt1_i32_b64 s2, s[2:3]
	v_mov_b32_e32 v0, 0x2000
	v_mov_b32_e32 v1, s2
	s_nop 0

.LBB0_251:
	s_or_b64 exec, exec, s[10:11]
	v_cvt_f32_u32_e32 v5, v3
	s_waitcnt vmcnt(0)
	v_readfirstlane_b32 s8, v4
	v_sub_u32_e32 v4, 0, v3
	v_rcp_iflag_f32_e32 v5, v5
	v_add_u32_e32 v6, s8, v1
	v_mul_f32_e32 v5, 0x4f7ffffe, v5
	v_cvt_u32_f32_e32 v5, v5
	v_mul_lo_u32 v1, v4, v5
	v_mul_hi_u32 v1, v5, v1
	v_add_u32_e32 v1, v5, v1
	v_mul_hi_u32 v1, v6, v1
	v_mul_lo_u32 v4, v1, v3
	v_sub_u32_e32 v4, v6, v4
	v_add_u32_e32 v5, 1, v1
	v_cmp_ge_u32_e32 vcc, v4, v3
	s_nop 1
	v_cndmask_b32_e32 v1, v1, v5, vcc
	v_sub_u32_e32 v5, v4, v3
	v_cndmask_b32_e32 v4, v4, v5, vcc
	v_add_u32_e32 v5, 1, v1
	v_cmp_ge_u32_e32 vcc, v4, v3
	v_add_u32_e32 v4, 1, v6
	s_nop 0
	v_cndmask_b32_e32 v1, v1, v5, vcc
	v_mul_lo_u32 v5, v3, v1
	v_add_u32_e32 v3, v5, v3
	v_cmp_ne_u32_e32 vcc, v4, v3
	s_and_saveexec_b64 s[8:9], vcc
	s_xor_b64 s[8:9], exec, s[8:9]
	s_cbranch_execz .LBB0_265
	s_waitcnt lgkmcnt(0)
	s_add_u32 s14, s4, 0x3c3500
	s_addc_u32 s15, s5, 0
	v_mov_b32_e32 v2, 0
	global_load_dword v2, v2, s[14:15] sc1
	s_waitcnt vmcnt(0)
	v_cmp_eq_u32_e32 vcc, v2, v1
	s_and_saveexec_b64 s[10:11], vcc
	s_cbranch_execz .LBB0_264
	s_add_u32 s12, s4, 0x3c0200
	s_addc_u32 s13, s5, 0
	s_mov_b32 s26, 1
	s_mov_b64 s[16:17], 0
	s_branch .LBB0_255

.LBB0_282:
	s_or_b64 exec, exec, s[4:5]
	s_mov_b64 s[4:5], exec
	v_mbcnt_lo_u32_b32 v1, s4, 0
	v_mbcnt_hi_u32_b32 v1, s5, v1
	v_cmp_eq_u32_e32 vcc, 0, v1
	s_waitcnt vmcnt(0)
	buffer_inv sc1
	s_and_saveexec_b64 s[8:9], vcc
	s_cbranch_execz .LBB0_284
	s_bcnt1_i32_b64 s4, s[4:5]
	v_mov_b32_e32 v1, s4
	v_mov_b32_e32 v2, 0x2000
	s_nop 0

.LBB0_431:
	s_or_b64 exec, exec, s[12:13]
	v_cvt_f32_u32_e32 v5, v3
	s_waitcnt vmcnt(0)
	v_readfirstlane_b32 s8, v4
	v_sub_u32_e32 v4, 0, v3
	v_rcp_iflag_f32_e32 v5, v5
	v_add_u32_e32 v6, s8, v1
	v_mul_f32_e32 v5, 0x4f7ffffe, v5
	v_cvt_u32_f32_e32 v5, v5
	v_mul_lo_u32 v1, v4, v5
	v_mul_hi_u32 v1, v5, v1
	v_add_u32_e32 v1, v5, v1
	v_mul_hi_u32 v1, v6, v1
	v_mul_lo_u32 v4, v1, v3
	v_sub_u32_e32 v4, v6, v4
	v_add_u32_e32 v5, 1, v1
	v_cmp_ge_u32_e32 vcc, v4, v3
	s_nop 1
	v_cndmask_b32_e32 v1, v1, v5, vcc
	v_sub_u32_e32 v5, v4, v3
	v_cndmask_b32_e32 v4, v4, v5, vcc
	v_add_u32_e32 v5, 1, v1
	v_cmp_ge_u32_e32 vcc, v4, v3
	v_add_u32_e32 v4, 1, v6
	s_nop 0
	v_cndmask_b32_e32 v1, v1, v5, vcc
	v_mul_lo_u32 v5, v3, v1
	v_add_u32_e32 v3, v5, v3
	v_cmp_ne_u32_e32 vcc, v4, v3
	s_and_saveexec_b64 s[8:9], vcc
	s_xor_b64 s[8:9], exec, s[8:9]
	s_cbranch_execz .LBB0_445
	s_waitcnt lgkmcnt(0)
	s_add_u32 s16, s4, 0x3c3500
	s_addc_u32 s17, s5, 0
	v_mov_b32_e32 v2, 0
	global_load_dword v2, v2, s[16:17] sc1
	s_waitcnt vmcnt(0)
	v_cmp_eq_u32_e32 vcc, v2, v1
	s_and_saveexec_b64 s[12:13], vcc
	s_cbranch_execz .LBB0_444
	s_add_u32 s14, s4, 0x3c0200
	s_addc_u32 s15, s5, 0
	s_mov_b32 s28, 1
	s_mov_b64 s[18:19], 0
	s_branch .LBB0_435

.LBB0_1779:
	s_bcnt1_i32_b64 s4, s[4:5]
	v_mov_b32_e32 v1, s4
	v_mov_b32_e32 v2, 0x2000
	s_nop 0
	s_getpc_b64 s[98:99]
